# nt hint on P0b's x-row loads (64 MB streamed once in that phase)
# speedup vs baseline: 1.0239x; 1.0058x over previous
.LBB0_138:
	v_lshl_add_u64 v[2:3], s[36:37], 0, v[204:205]
	v_lshl_add_u64 v[4:5], s[70:71], 0, v[204:205]
	v_lshl_add_u64 v[10:11], s[62:63], 0, v[204:205]
	v_lshl_add_u64 v[70:71], s[56:57], 0, v[204:205]
	global_load_dwordx4 v[6:9], v[74:75], off
	global_load_dwordx4 v[66:69], v[2:3], off nt
	global_load_dwordx4 v[58:61], v[2:3], off offset:1024 nt
	global_load_dwordx4 v[54:57], v[2:3], off offset:3072 nt
	global_load_dwordx4 v[62:65], v[2:3], off offset:2048 nt
	global_load_dwordx4 v[50:53], v[4:5], off nt
	global_load_dwordx4 v[42:45], v[4:5], off offset:1024 nt
	global_load_dwordx4 v[38:41], v[4:5], off offset:3072 nt
	global_load_dwordx4 v[46:49], v[4:5], off offset:2048 nt
	global_load_dwordx4 v[34:37], v[10:11], off nt
	global_load_dwordx4 v[30:33], v[10:11], off offset:1024 nt
	global_load_dwordx4 v[26:29], v[10:11], off offset:2048 nt
	global_load_dwordx4 v[22:25], v[10:11], off offset:3072 nt
	global_load_dwordx4 v[18:21], v[70:71], off nt
	global_load_dwordx4 v[14:17], v[70:71], off offset:1024 nt
	s_nop 0
	global_load_dwordx4 v[10:13], v[70:71], off offset:2048 nt
	global_load_dwordx4 v[2:5], v[70:71], off offset:3072 nt
	s_ashr_i32 s0, s38, 13
	v_lshl_add_u64 v[72:73], s[60:61], 0, v[200:201]
	v_lshl_add_u64 v[76:77], s[68:69], 0, v[200:201]
	s_mul_i32 s8, s0, 0x1800
	v_add_co_u32_e32 v82, vcc, s33, v72
	v_add_co_u32_e64 v80, s[0:1], s33, v76
	s_ashr_i32 s9, s8, 31
	v_addc_co_u32_e32 v83, vcc, 0, v73, vcc
	v_addc_co_u32_e64 v81, vcc, 0, v77, s[0:1]
	s_lshl_b64 s[0:1], s[8:9], 2
	s_add_u32 s78, s28, s0
	s_addc_u32 s79, s29, s1
	v_lshl_add_u64 v[96:97], s[30:31], 0, v[200:201]
	s_add_u32 s80, s78, 0x1000
	v_add_co_u32_e64 v76, s[6:7], s33, v96
	s_addc_u32 s81, s79, 0
	s_nop 0
	v_addc_co_u32_e64 v77, vcc, 0, v97, s[6:7]
	global_load_dwordx4 v[70:73], v92, s[78:79]
	global_load_dwordx4 v[96:99], v92, s[80:81]
	s_add_i32 s0, s38, 0x800
	s_ashr_i32 s0, s0, 13
	s_mulk_i32 s0, 0x1800
	s_ashr_i32 s1, s0, 31
	s_lshl_b64 s[0:1], s[0:1], 2
	s_add_u32 s54, s28, s0
	s_addc_u32 s55, s29, s1
	s_add_u32 s74, s54, 0x1000
	s_addc_u32 s75, s55, 0
	s_add_i32 s0, s38, 0x1000
	s_ashr_i32 s0, s0, 13
	s_mulk_i32 s0, 0x1800
	s_ashr_i32 s1, s0, 31
	s_lshl_b64 s[0:1], s[0:1], 2
	s_add_u32 s66, s28, s0
	s_addc_u32 s67, s29, s1
	s_add_u32 s72, s66, 0x1000
	s_addc_u32 s73, s67, 0
	s_add_i32 s0, s38, 0x1800
	v_lshl_add_u64 v[78:79], s[58:59], 0, v[200:201]
	s_ashr_i32 s0, s0, 13
	v_add_co_u32_e64 v78, s[4:5], s33, v78
	s_mulk_i32 s0, 0x1800
	s_nop 0
	v_addc_co_u32_e64 v79, vcc, 0, v79, s[4:5]
	s_ashr_i32 s1, s0, 31
	s_lshl_b64 s[0:1], s[0:1], 2
	s_add_u32 s52, s28, s0
	s_addc_u32 s53, s29, s1
	s_add_u32 s64, s52, 0x1000
	s_addc_u32 s65, s53, 0
	s_add_u32 s30, s30, 0x1000000
	s_addc_u32 s31, s31, 0
	s_add_u32 s36, s36, 0x2000000
	s_addc_u32 s37, s37, 0
	s_add_u32 s56, s56, 0x2000000
	s_addc_u32 s57, s57, 0
	s_add_u32 s58, s58, 0x1000000
	s_waitcnt vmcnt(17)
	v_pk_mul_f32 v[100:101], v[68:69], v[68:69]
	v_pk_mul_f32 v[102:103], v[66:67], v[66:67]
	s_waitcnt vmcnt(16)
	v_pk_mul_f32 v[104:105], v[60:61], v[60:61]
	v_pk_mul_f32 v[106:107], v[58:59], v[58:59]
	s_waitcnt vmcnt(13)
	v_pk_mul_f32 v[112:113], v[52:53], v[52:53]
	v_pk_mul_f32 v[114:115], v[50:51], v[50:51]
	s_waitcnt vmcnt(12)
	v_pk_mul_f32 v[116:117], v[44:45], v[44:45]
	v_pk_mul_f32 v[118:119], v[42:43], v[42:43]
	v_mul_f32_e32 v109, v56, v56
	v_mul_f32_e32 v108, v63, v63
	v_mul_f32_e32 v110, v65, v65
	s_waitcnt vmcnt(10)
	v_mul_f32_e32 v120, v47, v47
	v_mul_f32_e32 v122, v49, v49
	s_waitcnt vmcnt(9)
	v_pk_mul_f32 v[124:125], v[36:37], v[36:37]
	v_pk_mul_f32 v[126:127], v[34:35], v[34:35]
	s_waitcnt vmcnt(8)
	v_pk_mul_f32 v[128:129], v[32:33], v[32:33]
	v_pk_mul_f32 v[130:131], v[30:31], v[30:31]
	v_pk_mov_b32 v[140:141], v[102:103], v[100:101] op_sel:[1,0]
	v_mov_b32_e32 v103, v101
	v_pk_mov_b32 v[100:101], v[106:107], v[104:105] op_sel:[1,0]
	v_mov_b32_e32 v107, v105
	v_pk_mov_b32 v[104:105], v[114:115], v[112:113] op_sel:[1,0]
	v_mov_b32_e32 v115, v113
	v_pk_mov_b32 v[112:113], v[118:119], v[116:117] op_sel:[1,0]
	v_mov_b32_e32 v119, v117
	v_mul_f32_e32 v144, v57, v57
	v_mul_f32_e32 v147, v40, v40
	v_mul_f32_e32 v149, v41, v41
	s_waitcnt vmcnt(5)
	v_pk_mul_f32 v[132:133], v[20:21], v[20:21]
	v_pk_mul_f32 v[134:135], v[18:19], v[18:19]
	s_waitcnt vmcnt(4)
	v_pk_mul_f32 v[136:137], v[16:17], v[16:17]
	v_pk_mul_f32 v[138:139], v[14:15], v[14:15]
	v_pk_mov_b32 v[116:117], v[126:127], v[124:125] op_sel:[1,0]
	v_mov_b32_e32 v127, v125
	v_pk_mov_b32 v[124:125], v[130:131], v[128:129] op_sel:[1,0]
	v_mov_b32_e32 v131, v129
	v_pk_add_f32 v[102:103], v[140:141], v[102:103]
	v_pk_add_f32 v[100:101], v[100:101], v[106:107]
	v_pk_fma_f32 v[106:107], v[62:63], v[62:63], v[108:109] op_sel_hi:[1,1,0]
	v_pk_add_f32 v[112:113], v[112:113], v[118:119]
	v_pk_fma_f32 v[110:111], v[64:65], v[64:65], v[110:111] op_sel_hi:[1,1,0]
	v_pk_fma_f32 v[118:119], v[46:47], v[46:47], v[120:121] op_sel_hi:[1,1,0]
	v_pk_fma_f32 v[120:121], v[48:49], v[48:49], v[122:123] op_sel_hi:[1,1,0]
	v_mul_f32_e32 v142, v54, v54
	v_mul_f32_e32 v143, v55, v55
	v_pk_mov_b32 v[128:129], v[134:135], v[132:133] op_sel:[1,0]
	v_mov_b32_e32 v135, v133
	v_pk_mov_b32 v[132:133], v[138:139], v[136:137] op_sel:[1,0]
	v_mul_f32_e32 v136, v27, v27
	v_mul_f32_e32 v140, v29, v29
	s_waitcnt vmcnt(2)
	global_load_dwordx4 v[158:161], v[74:75], off
	global_load_dwordx4 v[174:177], v92, s[80:81]
	global_load_dwordx4 v[190:193], v92, s[78:79]
	global_load_dwordx4 v[162:165], v[74:75], off offset:1024
	global_load_dwordx4 v[178:181], v93, s[80:81]
	global_load_dwordx4 v[194:197], v92, s[78:79] offset:1024
	global_load_dwordx4 v[166:169], v[74:75], off offset:2048
	global_load_dwordx4 v[182:185], v94, s[80:81]
	global_load_dwordx4 v[206:209], v92, s[78:79] offset:2048
	global_load_dwordx4 v[170:173], v[74:75], off offset:3072
	global_load_dwordx4 v[186:189], v95, s[80:81]
	global_load_dwordx4 v[210:213], v92, s[78:79] offset:3072
	v_mul_f32_e32 v141, v2, v2
	v_mov_b32_e32 v107, v109
	v_pk_add_f32 v[104:105], v[104:105], v[114:115]
	v_mov_b32_e32 v111, v144
	v_mov_b32_e32 v119, v147
	v_mov_b32_e32 v121, v149
	v_pk_add_f32 v[116:117], v[116:117], v[126:127]
	v_pk_add_f32 v[124:125], v[124:125], v[130:131]
	v_pk_add_f32 v[102:103], v[102:103], v[102:103] op_sel:[0,1] op_sel_hi:[1,0]
	v_pk_add_f32 v[100:101], v[100:101], v[100:101] op_sel:[0,1] op_sel_hi:[1,0]
	v_mul_f32_e32 v145, v38, v38
	v_mul_f32_e32 v146, v39, v39
	v_mul_f32_e32 v150, v22, v22
	v_mul_f32_e32 v151, v23, v23
	v_mul_f32_e32 v152, v24, v24
	v_mul_f32_e32 v153, v25, v25
	v_mov_b32_e32 v139, v137
	v_pk_fma_f32 v[122:123], v[26:27], v[26:27], v[136:137] op_sel_hi:[1,1,0]
	v_pk_fma_f32 v[136:137], v[28:29], v[28:29], v[140:141] op_sel_hi:[1,1,0]
	v_pk_add_f32 v[106:107], v[106:107], v[110:111]
	v_pk_add_f32 v[104:105], v[104:105], v[104:105] op_sel:[0,1] op_sel_hi:[1,0]
	v_pk_add_f32 v[110:111], v[112:113], v[112:113] op_sel:[0,1] op_sel_hi:[1,0]
	v_pk_add_f32 v[112:113], v[118:119], v[120:121]
	v_pk_add_f32 v[116:117], v[116:117], v[116:117] op_sel:[0,1] op_sel_hi:[1,0]
	v_pk_add_f32 v[118:119], v[124:125], v[124:125] op_sel:[0,1] op_sel_hi:[1,0]
	v_mov_b32_e32 v103, v142
	v_mov_b32_e32 v101, v143
	v_mov_b32_e32 v123, v152
	v_mov_b32_e32 v137, v153
	v_mov_b32_e32 v105, v145
	v_mov_b32_e32 v111, v146
	v_mov_b32_e32 v117, v150
	v_mov_b32_e32 v119, v151
	v_pk_add_f32 v[100:101], v[102:103], v[100:101]
	v_mul_f32_e32 v108, v11, v11
	v_mul_f32_e32 v114, v13, v13
	v_pk_add_f32 v[126:127], v[128:129], v[134:135]
	v_pk_add_f32 v[128:129], v[132:133], v[138:139]
	v_pk_add_f32 v[120:121], v[122:123], v[136:137]
	v_pk_add_f32 v[102:103], v[104:105], v[110:111]
	v_pk_add_f32 v[104:105], v[116:117], v[118:119]
	v_pk_add_f32 v[100:101], v[100:101], v[106:107]
	v_mul_f32_e32 v154, v3, v3
	v_mul_f32_e32 v155, v4, v4
	v_mul_f32_e32 v156, v5, v5
	v_pk_fma_f32 v[108:109], v[10:11], v[10:11], v[108:109] op_sel_hi:[1,1,0]
	v_pk_fma_f32 v[114:115], v[12:13], v[12:13], v[114:115] op_sel_hi:[1,1,0]
	v_pk_add_f32 v[122:123], v[126:127], v[126:127] op_sel:[0,1] op_sel_hi:[1,0]
	v_pk_add_f32 v[124:125], v[128:129], v[128:129] op_sel:[0,1] op_sel_hi:[1,0]
	v_pk_add_f32 v[102:103], v[102:103], v[112:113]
	v_pk_add_f32 v[104:105], v[104:105], v[120:121]
	v_add_f32_e32 v100, v100, v101
	v_mov_b32_e32 v109, v155
	v_mov_b32_e32 v115, v156
	v_mov_b32_e32 v123, v141
	v_mov_b32_e32 v125, v154
	v_add_f32_e32 v101, v102, v103
	v_add_f32_e32 v102, v104, v105
	ds_bpermute_b32 v104, v84, v100
	v_pk_add_f32 v[108:109], v[108:109], v[114:115]
	v_pk_add_f32 v[110:111], v[122:123], v[124:125]
	ds_bpermute_b32 v105, v84, v101
	v_pk_add_f32 v[106:107], v[110:111], v[108:109]
	s_waitcnt lgkmcnt(1)
	v_add_f32_e32 v100, v100, v104
	v_add_f32_e32 v103, v106, v107
	ds_bpermute_b32 v106, v84, v102
	ds_bpermute_b32 v104, v85, v100
	s_waitcnt lgkmcnt(2)
	v_add_f32_e32 v101, v101, v105
	ds_bpermute_b32 v105, v85, v101
	ds_bpermute_b32 v107, v84, v103
	s_waitcnt lgkmcnt(3)
	v_add_f32_e32 v102, v102, v106
	ds_bpermute_b32 v106, v85, v102
	s_waitcnt lgkmcnt(3)
	v_add_f32_e32 v100, v100, v104
	ds_bpermute_b32 v104, v86, v100
	s_waitcnt lgkmcnt(3)
	v_add_f32_e32 v101, v101, v105
	ds_bpermute_b32 v105, v86, v101
	s_waitcnt lgkmcnt(2)
	v_add_f32_e32 v102, v102, v106
	ds_bpermute_b32 v106, v86, v102
	s_waitcnt lgkmcnt(2)
	v_add_f32_e32 v100, v100, v104
	ds_bpermute_b32 v104, v87, v100
	s_waitcnt lgkmcnt(2)
	v_add_f32_e32 v101, v101, v105
	ds_bpermute_b32 v105, v87, v101
	s_waitcnt lgkmcnt(2)
	v_add_f32_e32 v102, v102, v106
	ds_bpermute_b32 v106, v87, v102
	s_waitcnt lgkmcnt(2)
	v_add_f32_e32 v100, v100, v104
	ds_bpermute_b32 v104, v88, v100
	s_waitcnt lgkmcnt(2)
	v_add_f32_e32 v101, v101, v105
	ds_bpermute_b32 v105, v88, v101
	s_waitcnt lgkmcnt(2)
	v_add_f32_e32 v102, v102, v106
	ds_bpermute_b32 v106, v88, v102
	s_waitcnt lgkmcnt(2)
	v_add_f32_e32 v100, v100, v104
	ds_bpermute_b32 v104, v89, v100
	v_add_f32_e32 v103, v103, v107
	s_waitcnt lgkmcnt(2)
	v_add_f32_e32 v101, v101, v105
	ds_bpermute_b32 v107, v85, v103
	s_waitcnt lgkmcnt(2)
	v_add_f32_e32 v102, v102, v106
	ds_bpermute_b32 v105, v89, v101
	ds_bpermute_b32 v106, v89, v102
	s_waitcnt lgkmcnt(3)
	v_add_f32_e32 v100, v100, v104
	v_fmamk_f32 v100, v100, 0x3a800000, v90
	s_waitcnt lgkmcnt(2)
	v_add_f32_e32 v103, v103, v107
	s_waitcnt lgkmcnt(1)
	v_add_f32_e32 v101, v101, v105
	v_cmp_gt_f32_e32 vcc, s3, v100
	v_mul_f32_e32 v104, 0x4f800000, v100
	ds_bpermute_b32 v107, v86, v103
	s_waitcnt lgkmcnt(1)
	v_add_f32_e32 v102, v102, v106
	v_fmamk_f32 v101, v101, 0x3a800000, v90
	v_cndmask_b32_e32 v100, v100, v104, vcc
	v_fmamk_f32 v102, v102, 0x3a800000, v90
	v_cmp_gt_f32_e64 s[0:1], s3, v101
	v_mul_f32_e32 v105, 0x4f800000, v101
	v_sqrt_f32_e32 v104, v100
	v_cmp_gt_f32_e64 s[4:5], s3, v102
	v_mul_f32_e32 v106, 0x4f800000, v102
	v_cndmask_b32_e64 v101, v101, v105, s[0:1]
	v_cndmask_b32_e64 v102, v102, v106, s[4:5]
	v_sqrt_f32_e32 v105, v101
	v_sqrt_f32_e32 v106, v102
	s_waitcnt lgkmcnt(0)
	v_add_f32_e32 v103, v103, v107
	v_add_u32_e32 v107, -1, v104
	v_add_u32_e32 v108, 1, v104
	v_fma_f32 v113, -v107, v104, v100
	v_add_u32_e32 v109, -1, v105
	v_fma_f32 v114, -v108, v104, v100
	v_cmp_ge_f32_e64 s[12:13], 0, v113
	v_add_u32_e32 v110, 1, v105
	v_add_u32_e32 v111, -1, v106
	v_fma_f32 v115, -v109, v105, v101
	v_cmp_lt_f32_e64 s[16:17], 0, v114
	v_cndmask_b32_e64 v104, v104, v107, s[12:13]
	v_add_u32_e32 v112, 1, v106
	v_fma_f32 v116, -v110, v105, v101
	v_fma_f32 v117, -v111, v106, v102
	v_cmp_ge_f32_e64 s[18:19], 0, v115
	v_cndmask_b32_e64 v104, v104, v108, s[16:17]
	v_fma_f32 v118, -v112, v106, v102
	v_cmp_lt_f32_e64 s[20:21], 0, v116
	v_cmp_ge_f32_e64 s[22:23], 0, v117
	v_cndmask_b32_e64 v105, v105, v109, s[18:19]
	v_mul_f32_e32 v107, 0x37800000, v104
	v_cmp_class_f32_e64 s[6:7], v100, v91
	v_cmp_lt_f32_e64 s[24:25], 0, v118
	v_cndmask_b32_e64 v106, v106, v111, s[22:23]
	v_cndmask_b32_e64 v105, v105, v110, s[20:21]
	v_cndmask_b32_e32 v104, v104, v107, vcc
	v_cndmask_b32_e64 v106, v106, v112, s[24:25]
	v_mul_f32_e32 v108, 0x37800000, v105
	v_cndmask_b32_e64 v100, v104, v100, s[6:7]
	v_cmp_class_f32_e64 s[8:9], v101, v91
	v_mul_f32_e32 v109, 0x37800000, v106
	v_cndmask_b32_e64 v105, v105, v108, s[0:1]
	v_div_scale_f32 v104, s[0:1], v100, v100, 1.0
	v_cmp_class_f32_e64 s[10:11], v102, v91
	v_cndmask_b32_e64 v106, v106, v109, s[4:5]
	v_cndmask_b32_e64 v101, v105, v101, s[8:9]
	v_rcp_f32_e32 v110, v104
	v_cndmask_b32_e64 v102, v106, v102, s[10:11]
	v_div_scale_f32 v106, s[0:1], v101, v101, 1.0
	v_div_scale_f32 v108, s[4:5], v102, v102, 1.0
	v_rcp_f32_e32 v111, v106
	v_rcp_f32_e32 v112, v108
	v_fma_f32 v113, -v104, v110, 1.0
	v_div_scale_f32 v105, vcc, 1.0, v100, 1.0
	v_fmac_f32_e32 v110, v113, v110
	v_fma_f32 v114, -v106, v111, 1.0
	v_mul_f32_e32 v113, v105, v110
	v_div_scale_f32 v107, s[0:1], 1.0, v101, 1.0
	v_fma_f32 v115, -v108, v112, 1.0
	v_fmac_f32_e32 v111, v114, v111
	v_fma_f32 v116, -v104, v113, v105
	v_div_scale_f32 v109, s[4:5], 1.0, v102, 1.0
	v_fmac_f32_e32 v112, v115, v112
	v_mul_f32_e32 v114, v107, v111
	v_fmac_f32_e32 v113, v116, v110
	v_mul_f32_e32 v115, v109, v112
	v_fma_f32 v117, -v106, v114, v107
	v_fma_f32 v104, -v104, v113, v105
	v_fma_f32 v118, -v108, v115, v109
	v_fmac_f32_e32 v114, v117, v111
	v_div_fmas_f32 v104, v104, v110, v113
	v_fmac_f32_e32 v115, v118, v112
	v_fma_f32 v105, -v106, v114, v107
	v_div_fixup_f32 v100, v104, v100, 1.0
	s_mov_b64 vcc, s[0:1]
	v_fma_f32 v106, -v108, v115, v109
	v_div_fmas_f32 v104, v105, v111, v114
	v_pk_mul_f32 v[68:69], v[68:69], v[100:101] op_sel_hi:[1,0]
	v_pk_mul_f32 v[66:67], v[66:67], v[100:101] op_sel_hi:[1,0]
	s_mov_b64 vcc, s[4:5]
	s_waitcnt vmcnt(0)
	v_pk_add_f32 v[98:99], v[98:99], 1.0 op_sel_hi:[1,0]
	v_pk_add_f32 v[96:97], v[96:97], 1.0 op_sel_hi:[1,0]
	v_pk_mul_f32 v[60:61], v[60:61], v[100:101] op_sel_hi:[1,0]
	v_pk_mul_f32 v[58:59], v[58:59], v[100:101] op_sel_hi:[1,0]
	v_pk_mul_f32 v[64:65], v[64:65], v[100:101] op_sel_hi:[1,0]
	v_pk_mul_f32 v[62:63], v[62:63], v[100:101] op_sel_hi:[1,0]
	v_pk_mul_f32 v[56:57], v[56:57], v[100:101] op_sel_hi:[1,0]
	v_pk_mul_f32 v[54:55], v[54:55], v[100:101] op_sel_hi:[1,0]
	v_div_fixup_f32 v100, v104, v101, 1.0
	v_div_fmas_f32 v104, v106, v112, v115
	v_pk_mul_f32 v[66:67], v[6:7], v[66:67]
	v_pk_mul_f32 v[8:9], v[8:9], v[68:69]
	v_pk_mul_f32 v[52:53], v[52:53], v[100:101] op_sel_hi:[1,0]
	v_pk_mul_f32 v[50:51], v[50:51], v[100:101] op_sel_hi:[1,0]
	v_pk_mul_f32 v[44:45], v[44:45], v[100:101] op_sel_hi:[1,0]
	v_pk_mul_f32 v[42:43], v[42:43], v[100:101] op_sel_hi:[1,0]
	v_pk_mul_f32 v[48:49], v[48:49], v[100:101] op_sel_hi:[1,0]
	v_pk_mul_f32 v[46:47], v[46:47], v[100:101] op_sel_hi:[1,0]
	v_pk_mul_f32 v[68:69], v[40:41], v[100:101] op_sel_hi:[1,0]
	v_pk_mul_f32 v[100:101], v[38:39], v[100:101] op_sel_hi:[1,0]
	v_div_fixup_f32 v6, v104, v102, 1.0
	v_pk_fma_f32 v[8:9], v[98:99], v[8:9], v[72:73]
	v_pk_fma_f32 v[38:39], v[96:97], v[66:67], v[70:71]
	v_pk_mul_f32 v[66:67], v[36:37], v[6:7] op_sel_hi:[1,0]
	v_pk_mul_f32 v[70:71], v[34:35], v[6:7] op_sel_hi:[1,0]
	v_pk_mul_f32 v[72:73], v[32:33], v[6:7] op_sel_hi:[1,0]
	v_pk_mul_f32 v[96:97], v[30:31], v[6:7] op_sel_hi:[1,0]
	v_cvt_pk_bf16_f32 v9, v8, v9
	v_cvt_pk_bf16_f32 v8, v38, v39
	global_store_dwordx2 v[82:83], v[8:9], off
	s_addc_u32 s59, s59, 0
	s_add_u32 s60, s60, 0x1000000
	s_addc_u32 s61, s61, 0
	s_add_u32 s62, s62, 0x2000000
	s_addc_u32 s63, s63, 0
	s_add_u32 s68, s68, 0x1000000
	s_addc_u32 s69, s69, 0
	s_add_u32 s70, s70, 0x2000000
	s_addc_u32 s71, s71, 0
	v_pk_mul_f32 v[8:9], v[162:163], v[58:59]
	v_pk_mul_f32 v[30:31], v[164:165], v[60:61]
	v_pk_add_f32 v[32:33], v[180:181], 1.0 op_sel_hi:[1,0]
	v_pk_add_f32 v[34:35], v[178:179], 1.0 op_sel_hi:[1,0]
	v_pk_fma_f32 v[30:31], v[32:33], v[30:31], v[196:197]
	v_pk_fma_f32 v[8:9], v[34:35], v[8:9], v[194:195]
	v_cvt_pk_bf16_f32 v8, v8, v9
	v_cvt_pk_bf16_f32 v9, v30, v31
	global_store_dwordx2 v[82:83], v[8:9], off offset:512
	v_pk_mul_f32 v[8:9], v[166:167], v[62:63]
	v_pk_mul_f32 v[30:31], v[168:169], v[64:65]
	v_pk_add_f32 v[32:33], v[184:185], 1.0 op_sel_hi:[1,0]
	v_pk_add_f32 v[34:35], v[182:183], 1.0 op_sel_hi:[1,0]
	v_pk_fma_f32 v[30:31], v[30:31], v[32:33], v[208:209]
	v_pk_fma_f32 v[8:9], v[8:9], v[34:35], v[206:207]
	v_cvt_pk_bf16_f32 v8, v8, v9
	v_cvt_pk_bf16_f32 v9, v30, v31
	global_store_dwordx2 v[82:83], v[8:9], off offset:1024
	v_pk_mul_f32 v[8:9], v[54:55], v[170:171]
	v_pk_mul_f32 v[30:31], v[56:57], v[172:173]
	v_pk_add_f32 v[32:33], v[188:189], 1.0 op_sel_hi:[1,0]
	v_pk_add_f32 v[34:35], v[186:187], 1.0 op_sel_hi:[1,0]
	v_pk_fma_f32 v[30:31], v[30:31], v[32:33], v[212:213]
	v_pk_fma_f32 v[8:9], v[8:9], v[34:35], v[210:211]
	v_cvt_pk_bf16_f32 v8, v8, v9
	v_cvt_pk_bf16_f32 v9, v30, v31
	global_store_dwordx2 v[82:83], v[8:9], off offset:1536
	v_pk_mul_f32 v[8:9], v[158:159], v[50:51]
	v_pk_mul_f32 v[30:31], v[160:161], v[52:53]
	v_pk_add_f32 v[32:33], v[176:177], 1.0 op_sel_hi:[1,0]
	v_pk_add_f32 v[34:35], v[174:175], 1.0 op_sel_hi:[1,0]
	v_pk_fma_f32 v[30:31], v[32:33], v[30:31], v[192:193]
	v_pk_fma_f32 v[8:9], v[34:35], v[8:9], v[190:191]
	v_cvt_pk_bf16_f32 v8, v8, v9
	v_cvt_pk_bf16_f32 v9, v30, v31
	global_store_dwordx2 v[80:81], v[8:9], off
	v_pk_mul_f32 v[8:9], v[162:163], v[42:43]
	v_pk_mul_f32 v[30:31], v[164:165], v[44:45]
	v_pk_add_f32 v[32:33], v[180:181], 1.0 op_sel_hi:[1,0]
	v_pk_add_f32 v[34:35], v[178:179], 1.0 op_sel_hi:[1,0]
	v_pk_fma_f32 v[30:31], v[32:33], v[30:31], v[196:197]
	v_pk_fma_f32 v[8:9], v[34:35], v[8:9], v[194:195]
	v_cvt_pk_bf16_f32 v8, v8, v9
	v_cvt_pk_bf16_f32 v9, v30, v31
	global_store_dwordx2 v[80:81], v[8:9], off offset:512
	v_pk_mul_f32 v[8:9], v[166:167], v[46:47]
	v_pk_mul_f32 v[30:31], v[168:169], v[48:49]
	v_pk_add_f32 v[32:33], v[184:185], 1.0 op_sel_hi:[1,0]
	v_pk_add_f32 v[34:35], v[182:183], 1.0 op_sel_hi:[1,0]
	v_pk_fma_f32 v[30:31], v[30:31], v[32:33], v[208:209]
	v_pk_fma_f32 v[8:9], v[8:9], v[34:35], v[206:207]
	v_cvt_pk_bf16_f32 v8, v8, v9
	v_cvt_pk_bf16_f32 v9, v30, v31
	global_store_dwordx2 v[80:81], v[8:9], off offset:1024
	v_pk_mul_f32 v[8:9], v[100:101], v[170:171]
	v_pk_mul_f32 v[30:31], v[68:69], v[172:173]
	v_pk_add_f32 v[32:33], v[188:189], 1.0 op_sel_hi:[1,0]
	v_pk_add_f32 v[34:35], v[186:187], 1.0 op_sel_hi:[1,0]
	v_pk_fma_f32 v[30:31], v[30:31], v[32:33], v[212:213]
	v_pk_fma_f32 v[8:9], v[8:9], v[34:35], v[210:211]
	v_cvt_pk_bf16_f32 v8, v8, v9
	v_cvt_pk_bf16_f32 v9, v30, v31
	global_store_dwordx2 v[80:81], v[8:9], off offset:1536
	v_pk_mul_f32 v[8:9], v[158:159], v[70:71]
	v_pk_mul_f32 v[30:31], v[160:161], v[66:67]
	v_pk_add_f32 v[32:33], v[176:177], 1.0 op_sel_hi:[1,0]
	v_pk_add_f32 v[34:35], v[174:175], 1.0 op_sel_hi:[1,0]
	v_pk_fma_f32 v[30:31], v[32:33], v[30:31], v[192:193]
	v_pk_fma_f32 v[8:9], v[34:35], v[8:9], v[190:191]
	v_cvt_pk_bf16_f32 v8, v8, v9
	v_cvt_pk_bf16_f32 v9, v30, v31
	global_store_dwordx2 v[78:79], v[8:9], off
	v_pk_mul_f32 v[8:9], v[162:163], v[96:97]
	v_pk_mul_f32 v[30:31], v[164:165], v[72:73]
	v_pk_add_f32 v[32:33], v[180:181], 1.0 op_sel_hi:[1,0]
	v_pk_add_f32 v[34:35], v[178:179], 1.0 op_sel_hi:[1,0]
	v_pk_fma_f32 v[30:31], v[32:33], v[30:31], v[196:197]
	v_pk_fma_f32 v[8:9], v[34:35], v[8:9], v[194:195]
	v_cvt_pk_bf16_f32 v8, v8, v9
	v_cvt_pk_bf16_f32 v9, v30, v31
	global_store_dwordx2 v[78:79], v[8:9], off offset:512
	ds_bpermute_b32 v7, v87, v103
	s_waitcnt lgkmcnt(0)
	v_add_f32_e32 v7, v103, v7
	v_pk_mul_f32 v[8:9], v[28:29], v[6:7] op_sel_hi:[1,0]
	v_pk_mul_f32 v[26:27], v[26:27], v[6:7] op_sel_hi:[1,0]
	v_pk_mul_f32 v[8:9], v[168:169], v[8:9]
	v_pk_mul_f32 v[26:27], v[166:167], v[26:27]
	v_pk_add_f32 v[28:29], v[184:185], 1.0 op_sel_hi:[1,0]
	v_pk_add_f32 v[30:31], v[182:183], 1.0 op_sel_hi:[1,0]
	v_pk_fma_f32 v[8:9], v[8:9], v[28:29], v[208:209]
	v_pk_fma_f32 v[26:27], v[26:27], v[30:31], v[206:207]
	v_cvt_pk_bf16_f32 v9, v8, v9
	v_cvt_pk_bf16_f32 v8, v26, v27
	global_store_dwordx2 v[78:79], v[8:9], off offset:1024
	ds_bpermute_b32 v8, v88, v7
	s_waitcnt lgkmcnt(0)
	v_add_f32_e32 v7, v7, v8
	ds_bpermute_b32 v8, v89, v7
	s_waitcnt lgkmcnt(0)
	v_add_f32_e32 v7, v7, v8
	v_fmamk_f32 v7, v7, 0x3a800000, v90
	v_cmp_gt_f32_e32 vcc, s3, v7
	v_mul_f32_e32 v8, 0x4f800000, v7
	s_nop 0
	v_cndmask_b32_e32 v38, v7, v8, vcc
	v_pk_mul_f32 v[8:9], v[24:25], v[6:7] op_sel_hi:[1,0]
	v_pk_mul_f32 v[6:7], v[22:23], v[6:7] op_sel_hi:[1,0]
	v_sqrt_f32_e32 v39, v38
	v_cmp_class_f32_e64 s[0:1], v38, v91
	v_pk_mul_f32 v[6:7], v[6:7], v[170:171]
	v_pk_mul_f32 v[8:9], v[8:9], v[172:173]
	v_pk_add_f32 v[22:23], v[188:189], 1.0 op_sel_hi:[1,0]
	v_pk_add_f32 v[24:25], v[186:187], 1.0 op_sel_hi:[1,0]
	v_pk_fma_f32 v[8:9], v[8:9], v[22:23], v[212:213]
	v_pk_fma_f32 v[6:7], v[6:7], v[24:25], v[210:211]
	v_cvt_pk_bf16_f32 v6, v6, v7
	v_cvt_pk_bf16_f32 v7, v8, v9
	global_store_dwordx2 v[78:79], v[6:7], off offset:1536
	v_add_u32_e32 v6, -1, v39
	v_add_u32_e32 v7, 1, v39
	v_fma_f32 v8, -v6, v39, v38
	v_fma_f32 v9, -v7, v39, v38
	v_cmp_ge_f32_e64 s[4:5], 0, v8
	v_cmp_lt_f32_e64 s[6:7], 0, v9
	s_nop 0
	v_cndmask_b32_e64 v6, v39, v6, s[4:5]
	v_cndmask_b32_e64 v6, v6, v7, s[6:7]
	v_mul_f32_e32 v7, 0x37800000, v6
	v_cndmask_b32_e32 v6, v6, v7, vcc
	v_cndmask_b32_e64 v6, v6, v38, s[0:1]
	v_div_scale_f32 v7, s[0:1], v6, v6, 1.0
	v_rcp_f32_e32 v9, v7
	v_div_scale_f32 v8, vcc, 1.0, v6, 1.0
	s_add_i32 s0, s38, 0x2000
	v_fma_f32 v34, -v7, v9, 1.0
	v_fmac_f32_e32 v9, v34, v9
	v_mul_f32_e32 v34, v8, v9
	v_fma_f32 v35, -v7, v34, v8
	v_fmac_f32_e32 v34, v35, v9
	v_fma_f32 v7, -v7, v34, v8
	v_div_fmas_f32 v7, v7, v9, v34
	v_div_fixup_f32 v6, v7, v6, 1.0
	v_pk_mul_f32 v[8:9], v[20:21], v[6:7] op_sel_hi:[1,0]
	v_pk_mul_f32 v[18:19], v[18:19], v[6:7] op_sel_hi:[1,0]
	s_cmpk_lt_i32 s38, 0x2000
	s_mov_b32 s38, s0
	v_pk_mul_f32 v[18:19], v[158:159], v[18:19]
	v_pk_mul_f32 v[8:9], v[160:161], v[8:9]
	v_pk_add_f32 v[20:21], v[176:177], 1.0 op_sel_hi:[1,0]
	v_pk_add_f32 v[22:23], v[174:175], 1.0 op_sel_hi:[1,0]
	v_pk_fma_f32 v[8:9], v[20:21], v[8:9], v[192:193]
	v_pk_fma_f32 v[18:19], v[22:23], v[18:19], v[190:191]
	v_bfe_u32 v21, v8, 16, 1
	v_bfe_u32 v7, v18, 16, 1
	v_bfe_u32 v20, v19, 16, 1
	v_bfe_u32 v22, v9, 16, 1
	v_add3_u32 v7, v18, v7, s26
	v_add3_u32 v8, v8, v21, s26
	v_add3_u32 v18, v19, v20, s26
	v_add3_u32 v9, v9, v22, s26
	v_lshrrev_b32_e32 v7, 16, v7
	v_lshrrev_b32_e32 v19, 16, v8
	v_and_or_b32 v8, v18, s27, v7
	v_and_or_b32 v9, v9, s27, v19
	global_store_dwordx2 v[76:77], v[8:9], off
	v_pk_mul_f32 v[8:9], v[16:17], v[6:7] op_sel_hi:[1,0]
	v_pk_mul_f32 v[14:15], v[14:15], v[6:7] op_sel_hi:[1,0]
	v_pk_mul_f32 v[8:9], v[164:165], v[8:9]
	v_pk_mul_f32 v[14:15], v[162:163], v[14:15]
	v_pk_add_f32 v[16:17], v[180:181], 1.0 op_sel_hi:[1,0]
	v_pk_add_f32 v[18:19], v[178:179], 1.0 op_sel_hi:[1,0]
	v_pk_fma_f32 v[8:9], v[16:17], v[8:9], v[196:197]
	v_pk_fma_f32 v[14:15], v[18:19], v[14:15], v[194:195]
	v_bfe_u32 v17, v8, 16, 1
	v_bfe_u32 v7, v14, 16, 1
	v_bfe_u32 v16, v15, 16, 1
	v_bfe_u32 v18, v9, 16, 1
	v_add3_u32 v7, v14, v7, s26
	v_add3_u32 v8, v8, v17, s26
	v_add3_u32 v14, v15, v16, s26
	v_add3_u32 v9, v9, v18, s26
	v_lshrrev_b32_e32 v7, 16, v7
	v_lshrrev_b32_e32 v15, 16, v8
	v_and_or_b32 v8, v14, s27, v7
	v_and_or_b32 v9, v9, s27, v15
	global_store_dwordx2 v[76:77], v[8:9], off offset:512
	v_pk_mul_f32 v[8:9], v[12:13], v[6:7] op_sel_hi:[1,0]
	v_pk_mul_f32 v[10:11], v[10:11], v[6:7] op_sel_hi:[1,0]
	v_pk_mul_f32 v[8:9], v[168:169], v[8:9]
	v_pk_mul_f32 v[10:11], v[166:167], v[10:11]
	v_pk_add_f32 v[12:13], v[184:185], 1.0 op_sel_hi:[1,0]
	v_pk_add_f32 v[14:15], v[182:183], 1.0 op_sel_hi:[1,0]
	v_pk_fma_f32 v[8:9], v[8:9], v[12:13], v[208:209]
	v_pk_fma_f32 v[10:11], v[10:11], v[14:15], v[206:207]
	v_bfe_u32 v13, v8, 16, 1
	v_bfe_u32 v7, v10, 16, 1
	v_bfe_u32 v12, v11, 16, 1
	v_bfe_u32 v14, v9, 16, 1
	v_add3_u32 v7, v10, v7, s26
	v_add3_u32 v8, v8, v13, s26
	v_add3_u32 v10, v11, v12, s26
	v_add3_u32 v9, v9, v14, s26
	v_lshrrev_b32_e32 v7, 16, v7
	v_lshrrev_b32_e32 v11, 16, v8
	v_and_or_b32 v8, v10, s27, v7
	v_and_or_b32 v9, v9, s27, v11
	global_store_dwordx2 v[76:77], v[8:9], off offset:1024
	s_nop 0
	v_pk_mul_f32 v[4:5], v[4:5], v[6:7] op_sel_hi:[1,0]
	v_pk_mul_f32 v[2:3], v[2:3], v[6:7] op_sel_hi:[1,0]
	v_pk_mul_f32 v[4:5], v[4:5], v[172:173]
	v_pk_mul_f32 v[2:3], v[2:3], v[170:171]
	v_pk_add_f32 v[6:7], v[188:189], 1.0 op_sel_hi:[1,0]
	v_pk_add_f32 v[8:9], v[186:187], 1.0 op_sel_hi:[1,0]
	v_pk_fma_f32 v[4:5], v[4:5], v[6:7], v[212:213]
	v_pk_fma_f32 v[2:3], v[2:3], v[8:9], v[210:211]
	v_cvt_pk_bf16_f32 v2, v2, v3
	v_cvt_pk_bf16_f32 v3, v4, v5
	global_store_dwordx2 v[76:77], v[2:3], off offset:1536
	s_cbranch_scc1 .LBB0_138
	v_readlane_b32 s16, v251, 9
	v_readlane_b32 s17, v251, 10
	v_readlane_b32 s18, v251, 11
	v_readlane_b32 s19, v251, 12
	v_readlane_b32 s20, v251, 13
	v_readlane_b32 s21, v251, 14
	v_readlane_b32 s22, v251, 15
	v_readlane_b32 s23, v251, 16
	v_readlane_b32 s24, v251, 17
	v_readlane_b32 s25, v251, 18
	v_readlane_b32 s26, v251, 19
	v_readlane_b32 s27, v251, 20
	v_readlane_b32 s28, v251, 21
	v_readlane_b32 s29, v251, 22
	v_readlane_b32 s30, v251, 23
	v_readlane_b32 s31, v251, 24
	v_readlane_b32 s16, v251, 25
	v_readlane_b32 s17, v251, 26
	v_readlane_b32 s18, v251, 27
	v_readlane_b32 s19, v251, 28
	v_readlane_b32 s20, v251, 29
	v_readlane_b32 s21, v251, 30
	v_readlane_b32 s22, v251, 31
	v_readlane_b32 s23, v251, 32
	v_readlane_b32 s24, v251, 33
	v_readlane_b32 s25, v251, 34
	v_readlane_b32 s26, v251, 35
	v_readlane_b32 s27, v251, 36
	v_readlane_b32 s28, v251, 37
	v_readlane_b32 s29, v251, 38
	v_readlane_b32 s30, v251, 39
	v_readlane_b32 s31, v251, 40
